# P0 w_up transpose items: eight row loads + eight scale loads issued before first wait (was one load in flight at a time)
# speedup vs baseline: 1.0000x; 1.0000x over previous
.LBB0_19:
	s_andn2_b64 vcc, exec, s[4:5]
	s_cbranch_vccnz .LBB0_38
	s_add_i32 s0, s28, 0xa000
	s_lshr_b32 s0, s0, 3
	s_and_b32 s17, s0, 0x1fc0
	s_and_b32 s16, s9, 0x3fe0
	s_lshl_b32 s0, s16, 2
	v_or_b32_e32 v6, s17, v1
	v_lshl_add_u64 v[40:41], v[18:19], 0, s[0:1]
	v_lshlrev_b32_e32 v14, 16, v6
	v_add_lshl_u32 v39, s17, v1, 2
	v_lshl_add_u64 v[4:5], v[40:41], 0, v[14:15]
	global_load_dwordx4 v[4:7], v[4:5], off
	v_or_b32_sdwa v14, s17, v17 dst_sel:WORD_1 dst_unused:UNUSED_PAD src0_sel:DWORD src1_sel:DWORD
	s_nop 0
	v_lshl_add_u64 v[8:9], v[40:41], 0, v[14:15]
	global_load_dwordx4 v[8:11], v[8:9], off
	v_or_b32_sdwa v14, s17, v42 dst_sel:WORD_1 dst_unused:UNUSED_PAD src0_sel:DWORD src1_sel:DWORD
	s_nop 0
	v_lshl_add_u64 v[60:61], v[40:41], 0, v[14:15]
	global_load_dwordx4 v[60:63], v[60:61], off
	v_or_b32_sdwa v14, s17, v43 dst_sel:WORD_1 dst_unused:UNUSED_PAD src0_sel:DWORD src1_sel:DWORD
	s_nop 0
	v_lshl_add_u64 v[64:65], v[40:41], 0, v[14:15]
	global_load_dwordx4 v[64:67], v[64:65], off
	v_or_b32_sdwa v14, s17, v44 dst_sel:WORD_1 dst_unused:UNUSED_PAD src0_sel:DWORD src1_sel:DWORD
	s_nop 0
	v_lshl_add_u64 v[68:69], v[40:41], 0, v[14:15]
	global_load_dwordx4 v[68:71], v[68:69], off
	v_or_b32_sdwa v14, s17, v45 dst_sel:WORD_1 dst_unused:UNUSED_PAD src0_sel:DWORD src1_sel:DWORD
	s_nop 0
	v_lshl_add_u64 v[72:73], v[40:41], 0, v[14:15]
	global_load_dwordx4 v[72:75], v[72:73], off
	v_or_b32_sdwa v14, s17, v46 dst_sel:WORD_1 dst_unused:UNUSED_PAD src0_sel:DWORD src1_sel:DWORD
	s_nop 0
	v_lshl_add_u64 v[76:77], v[40:41], 0, v[14:15]
	global_load_dwordx4 v[76:79], v[76:77], off
	v_or_b32_sdwa v14, s17, v47 dst_sel:WORD_1 dst_unused:UNUSED_PAD src0_sel:DWORD src1_sel:DWORD
	s_nop 0
	v_lshl_add_u64 v[80:81], v[40:41], 0, v[14:15]
	global_load_dwordx4 v[80:83], v[80:81], off
	s_and_b64 vcc, exec, s[12:13]
	s_cbranch_vccz .Lwup_noscale
	v_readlane_b32 s46, v249, 30
	v_readlane_b32 s47, v249, 31
	v_readlane_b32 s36, v249, 20
	v_readlane_b32 s37, v249, 21
	v_readlane_b32 s38, v249, 22
	v_readlane_b32 s39, v249, 23
	v_readlane_b32 s40, v249, 24
	v_readlane_b32 s41, v249, 25
	v_readlane_b32 s42, v249, 26
	v_readlane_b32 s43, v249, 27
	v_readlane_b32 s44, v249, 28
	v_readlane_b32 s45, v249, 29
	v_readlane_b32 s48, v249, 32
	v_readlane_b32 s49, v249, 33
	v_readlane_b32 s50, v249, 34
	v_readlane_b32 s51, v249, 35
	global_load_dword v2, v39, s[46:47]
	s_nop 0
	global_load_dword v3, v39, s[46:47] offset:32
	s_nop 0
	global_load_dword v12, v39, s[46:47] offset:64
	s_nop 0
	global_load_dword v13, v39, s[46:47] offset:96
	s_nop 0
	global_load_dword v14, v39, s[46:47] offset:128
	s_nop 0
	global_load_dword v40, v39, s[46:47] offset:160
	s_nop 0
	global_load_dword v41, v39, s[46:47] offset:192
	s_nop 0
	global_load_dword v39, v39, s[46:47] offset:224
	s_waitcnt vmcnt(0)
	v_mul_f32_e32 v4, v2, v4
	v_mul_f32_e32 v5, v2, v5
	v_mul_f32_e32 v6, v2, v6
	v_mul_f32_e32 v7, v2, v7
	v_mul_f32_e32 v8, v3, v8
	v_mul_f32_e32 v9, v3, v9
	v_mul_f32_e32 v10, v3, v10
	v_mul_f32_e32 v11, v3, v11
	v_mul_f32_e32 v60, v12, v60
	v_mul_f32_e32 v61, v12, v61
	v_mul_f32_e32 v62, v12, v62
	v_mul_f32_e32 v63, v12, v63
	v_mul_f32_e32 v64, v13, v64
	v_mul_f32_e32 v65, v13, v65
	v_mul_f32_e32 v66, v13, v66
	v_mul_f32_e32 v67, v13, v67
	v_mul_f32_e32 v68, v14, v68
	v_mul_f32_e32 v69, v14, v69
	v_mul_f32_e32 v70, v14, v70
	v_mul_f32_e32 v71, v14, v71
	v_mul_f32_e32 v72, v40, v72
	v_mul_f32_e32 v73, v40, v73
	v_mul_f32_e32 v74, v40, v74
	v_mul_f32_e32 v75, v40, v75
	v_mul_f32_e32 v76, v41, v76
	v_mul_f32_e32 v77, v41, v77
	v_mul_f32_e32 v78, v41, v78
	v_mul_f32_e32 v79, v41, v79
	v_mul_f32_e32 v80, v39, v80
	v_mul_f32_e32 v81, v39, v81
	v_mul_f32_e32 v82, v39, v82
	v_mul_f32_e32 v83, v39, v83
.Lwup_noscale:
	s_waitcnt vmcnt(0)
	v_add_u32_e32 v2, 0x18c0, v49
	v_add_u32_e32 v3, 0x18c8, v49
	v_add_u32_e32 v12, 0x1ce0, v49
	v_add_u32_e32 v13, 0x1ce8, v49
	ds_write2_b32 v49, v4, v5 offset1:1
	ds_write2_b32 v49, v6, v7 offset0:2 offset1:3
	ds_write2_b32 v50, v8, v9 offset1:1
	ds_write2_b32 v51, v10, v11 offset1:1
	ds_write2_b32 v52, v60, v61 offset1:1
	ds_write2_b32 v53, v62, v63 offset1:1
	ds_write2_b32 v54, v64, v65 offset1:1
	ds_write2_b32 v55, v66, v67 offset1:1
	ds_write2_b32 v56, v68, v69 offset1:1
	ds_write2_b32 v57, v70, v71 offset1:1
	ds_write2_b32 v58, v72, v73 offset1:1
	ds_write2_b32 v59, v74, v75 offset1:1
	ds_write2_b32 v2, v76, v77 offset1:1
	ds_write2_b32 v3, v78, v79 offset1:1
	ds_write2_b32 v12, v80, v81 offset1:1
	ds_write2_b32 v13, v82, v83 offset1:1
	s_waitcnt lgkmcnt(0)
	ds_read2_b32 v[2:3], v48 offset1:33
	s_waitcnt lgkmcnt(0)
	v_cvt_pk_bf16_f32 v2, v2, v3
	ds_read2_b32 v[4:5], v48 offset0:66 offset1:99
	s_lshl_b32 s0, s17, 1
	v_or_b32_e32 v10, s16, v1
	s_waitcnt lgkmcnt(0)
	v_cvt_pk_bf16_f32 v3, v4, v5
	ds_read2_b32 v[4:5], v48 offset0:132 offset1:165
	v_lshl_add_u64 v[8:9], v[20:21], 0, s[0:1]
	v_lshlrev_b32_e32 v14, 13, v10
	s_waitcnt lgkmcnt(0)
	v_cvt_pk_bf16_f32 v4, v4, v5
	ds_read2_b32 v[6:7], v48 offset0:198 offset1:231
	s_waitcnt lgkmcnt(0)
	v_cvt_pk_bf16_f32 v5, v6, v7
	v_lshl_add_u64 v[10:11], v[8:9], 0, v[14:15]
	ds_read2_b32 v[6:7], v48 offset0:8 offset1:41
	global_store_dwordx4 v[10:11], v[2:5], off
	v_or_b32_e32 v10, s16, v17
	v_lshlrev_b32_e32 v14, 13, v10
	s_waitcnt lgkmcnt(0)
	v_cvt_pk_bf16_f32 v2, v6, v7
	ds_read2_b32 v[4:5], v48 offset0:74 offset1:107
	s_waitcnt lgkmcnt(0)
	v_cvt_pk_bf16_f32 v3, v4, v5
	ds_read2_b32 v[4:5], v48 offset0:140 offset1:173
	s_waitcnt lgkmcnt(0)
	v_cvt_pk_bf16_f32 v4, v4, v5
	ds_read2_b32 v[6:7], v48 offset0:206 offset1:239
	s_waitcnt lgkmcnt(0)
	v_cvt_pk_bf16_f32 v5, v6, v7
	v_lshl_add_u64 v[10:11], v[8:9], 0, v[14:15]
	ds_read2_b32 v[6:7], v48 offset0:16 offset1:49
	global_store_dwordx4 v[10:11], v[2:5], off
	v_or_b32_e32 v10, s16, v42
	v_lshlrev_b32_e32 v14, 13, v10
	s_waitcnt lgkmcnt(0)
	v_cvt_pk_bf16_f32 v2, v6, v7
	ds_read2_b32 v[4:5], v48 offset0:82 offset1:115
	s_waitcnt lgkmcnt(0)
	v_cvt_pk_bf16_f32 v3, v4, v5
	ds_read2_b32 v[4:5], v48 offset0:148 offset1:181
	s_waitcnt lgkmcnt(0)
	v_cvt_pk_bf16_f32 v4, v4, v5
	ds_read2_b32 v[6:7], v48 offset0:214 offset1:247
	s_waitcnt lgkmcnt(0)
	v_cvt_pk_bf16_f32 v5, v6, v7
	v_lshl_add_u64 v[10:11], v[8:9], 0, v[14:15]
	ds_read2_b32 v[6:7], v48 offset0:24 offset1:57
	global_store_dwordx4 v[10:11], v[2:5], off
	s_waitcnt lgkmcnt(0)
	s_nop 0
	v_cvt_pk_bf16_f32 v2, v6, v7
	ds_read2_b32 v[4:5], v48 offset0:90 offset1:123
	s_waitcnt lgkmcnt(0)
	v_cvt_pk_bf16_f32 v3, v4, v5
	ds_read2_b32 v[4:5], v48 offset0:156 offset1:189
	s_waitcnt lgkmcnt(0)
	v_cvt_pk_bf16_f32 v4, v4, v5
	v_or_b32_e32 v5, s16, v43
	ds_read2_b32 v[6:7], v48 offset0:222 offset1:255
	v_lshlrev_b32_e32 v14, 13, v5
	s_waitcnt lgkmcnt(0)
	v_cvt_pk_bf16_f32 v5, v6, v7
	v_lshl_add_u64 v[6:7], v[8:9], 0, v[14:15]
	global_store_dwordx4 v[6:7], v[2:5], off
	s_waitcnt lgkmcnt(0)

.LBB0_42:
	s_andn2_b64 vcc, exec, s[4:5]
	s_cbranch_vccnz .LBB0_10
	s_ashr_i32 s0, s28, 31
	s_lshr_b32 s0, s0, 24
	s_add_i32 s0, s28, s0
	s_ashr_i32 s0, s0, 8
	s_lshl_b32 s16, s0, 6
	s_lshl_b32 s0, s0, 13
	s_sub_i32 s4, s9, s0
	v_or_b32_e32 v2, s16, v1
	v_or_b32_e32 v4, s16, v17
	v_or_b32_e32 v10, s16, v42
	v_or_b32_e32 v12, s16, v43
	v_or_b32_e32 v64, s16, v44
	v_or_b32_e32 v66, s16, v45
	s_ashr_i32 s5, s4, 31
	v_ashrrev_i32_e32 v3, 31, v2
	v_ashrrev_i32_e32 v5, 31, v4
	v_ashrrev_i32_e32 v11, 31, v10
	v_ashrrev_i32_e32 v13, 31, v12
	v_ashrrev_i32_e32 v65, 31, v64
	v_ashrrev_i32_e32 v67, 31, v66
	v_lshl_add_u64 v[40:41], s[4:5], 2, v[26:27]
	v_lshlrev_b64 v[2:3], 15, v[2:3]
	v_lshlrev_b64 v[4:5], 15, v[4:5]
	v_lshlrev_b64 v[10:11], 15, v[10:11]
	v_lshlrev_b64 v[12:13], 15, v[12:13]
	v_lshlrev_b64 v[64:65], 15, v[64:65]
	v_lshlrev_b64 v[66:67], 15, v[66:67]
	v_lshl_add_u64 v[2:3], v[40:41], 0, v[2:3]
	v_lshl_add_u64 v[6:7], v[40:41], 0, v[4:5]
	v_lshl_add_u64 v[10:11], v[40:41], 0, v[10:11]
	v_lshl_add_u64 v[60:61], v[40:41], 0, v[12:13]
	v_lshl_add_u64 v[64:65], v[40:41], 0, v[64:65]
	v_lshl_add_u64 v[68:69], v[40:41], 0, v[66:67]
	global_load_dwordx4 v[2:5], v[2:3], off
	s_nop 0
	global_load_dwordx4 v[6:9], v[6:7], off
	s_nop 0
	global_load_dwordx4 v[10:13], v[10:11], off
	s_nop 0
	global_load_dwordx4 v[60:63], v[60:61], off
	s_nop 0
	global_load_dwordx4 v[64:67], v[64:65], off
	s_nop 0
	global_load_dwordx4 v[68:71], v[68:69], off
	v_or_b32_e32 v72, s16, v46
	v_ashrrev_i32_e32 v73, 31, v72
	v_lshlrev_b64 v[72:73], 15, v[72:73]
	v_or_b32_e32 v76, s16, v47
	v_lshl_add_u64 v[72:73], v[40:41], 0, v[72:73]
	v_ashrrev_i32_e32 v77, 31, v76
	global_load_dwordx4 v[72:75], v[72:73], off
	v_lshlrev_b64 v[76:77], 15, v[76:77]
	v_lshl_add_u64 v[40:41], v[40:41], 0, v[76:77]
	global_load_dwordx4 v[76:79], v[40:41], off
	v_add_u32_e32 v14, 0x18c0, v49
	v_add_u32_e32 v39, 0x18c8, v49
	v_add_u32_e32 v40, 0x1ce0, v49
	v_add_u32_e32 v41, 0x1ce8, v49
	s_ashr_i32 s17, s16, 31
	s_waitcnt vmcnt(7)
	ds_write2_b32 v49, v2, v3 offset1:1
	ds_write2_b32 v49, v4, v5 offset0:2 offset1:3
	s_waitcnt vmcnt(6)
	ds_write2_b32 v50, v6, v7 offset1:1
	ds_write2_b32 v51, v8, v9 offset1:1
	s_waitcnt vmcnt(5)
	ds_write2_b32 v52, v10, v11 offset1:1
	ds_write2_b32 v53, v12, v13 offset1:1
	s_waitcnt vmcnt(4)
	ds_write2_b32 v54, v60, v61 offset1:1
	ds_write2_b32 v55, v62, v63 offset1:1
	s_waitcnt vmcnt(3)
	ds_write2_b32 v56, v64, v65 offset1:1
	ds_write2_b32 v57, v66, v67 offset1:1
	s_waitcnt vmcnt(2)
	ds_write2_b32 v58, v68, v69 offset1:1
	ds_write2_b32 v59, v70, v71 offset1:1
	s_waitcnt vmcnt(1)
	ds_write2_b32 v14, v72, v73 offset1:1
	ds_write2_b32 v39, v74, v75 offset1:1
	s_waitcnt vmcnt(0)
	ds_write2_b32 v40, v76, v77 offset1:1
	ds_write2_b32 v41, v78, v79 offset1:1
	s_waitcnt lgkmcnt(0)
	v_add_u32_e32 v10, s4, v1
	ds_read2_b32 v[2:3], v48 offset1:33
	v_ashrrev_i32_e32 v11, 31, v10
	s_waitcnt lgkmcnt(0)
	v_cvt_pk_bf16_f32 v2, v2, v3
	ds_read2_b32 v[4:5], v48 offset0:66 offset1:99
	v_lshl_add_u64 v[8:9], s[16:17], 1, v[28:29]
	v_lshlrev_b64 v[12:13], 13, v[10:11]
	s_waitcnt lgkmcnt(0)
	v_cvt_pk_bf16_f32 v3, v4, v5
	ds_read2_b32 v[4:5], v48 offset0:132 offset1:165
	v_lshl_add_u64 v[12:13], v[8:9], 0, v[12:13]
	s_waitcnt lgkmcnt(0)
	v_cvt_pk_bf16_f32 v4, v4, v5
	ds_read2_b32 v[6:7], v48 offset0:198 offset1:231
	s_waitcnt lgkmcnt(0)
	v_cvt_pk_bf16_f32 v5, v6, v7
	global_store_dwordx4 v[12:13], v[2:5], off
	v_add_u32_e32 v12, 8, v10
	v_ashrrev_i32_e32 v13, 31, v12
	ds_read2_b32 v[6:7], v48 offset0:8 offset1:41
	s_waitcnt lgkmcnt(0)
	v_cvt_pk_bf16_f32 v2, v6, v7
	ds_read2_b32 v[4:5], v48 offset0:74 offset1:107
	v_lshlrev_b64 v[12:13], 13, v[12:13]
	s_waitcnt lgkmcnt(0)
	v_cvt_pk_bf16_f32 v3, v4, v5
	ds_read2_b32 v[4:5], v48 offset0:140 offset1:173
	v_lshl_add_u64 v[12:13], v[8:9], 0, v[12:13]
	s_waitcnt lgkmcnt(0)
	v_cvt_pk_bf16_f32 v4, v4, v5
	ds_read2_b32 v[6:7], v48 offset0:206 offset1:239
	s_waitcnt lgkmcnt(0)
	v_cvt_pk_bf16_f32 v5, v6, v7
	global_store_dwordx4 v[12:13], v[2:5], off
	v_add_u32_e32 v12, 16, v10
	ds_read2_b32 v[6:7], v48 offset0:16 offset1:49
	s_waitcnt lgkmcnt(0)
	v_cvt_pk_bf16_f32 v2, v6, v7
	ds_read2_b32 v[4:5], v48 offset0:82 offset1:115
	v_ashrrev_i32_e32 v13, 31, v12
	s_waitcnt lgkmcnt(0)
	v_cvt_pk_bf16_f32 v3, v4, v5
	ds_read2_b32 v[4:5], v48 offset0:148 offset1:181
	v_lshlrev_b64 v[12:13], 13, v[12:13]
	s_waitcnt lgkmcnt(0)
	v_cvt_pk_bf16_f32 v4, v4, v5
	ds_read2_b32 v[6:7], v48 offset0:214 offset1:247
	s_waitcnt lgkmcnt(0)
	v_cvt_pk_bf16_f32 v5, v6, v7
	v_lshl_add_u64 v[12:13], v[8:9], 0, v[12:13]
	ds_read2_b32 v[6:7], v48 offset0:24 offset1:57
	global_store_dwordx4 v[12:13], v[2:5], off
	v_add_u32_e32 v10, 24, v10
	v_ashrrev_i32_e32 v11, 31, v10
	s_waitcnt lgkmcnt(0)
	v_cvt_pk_bf16_f32 v2, v6, v7
	ds_read2_b32 v[4:5], v48 offset0:90 offset1:123
	s_waitcnt lgkmcnt(0)
	v_cvt_pk_bf16_f32 v3, v4, v5
	ds_read2_b32 v[4:5], v48 offset0:156 offset1:189
	s_waitcnt lgkmcnt(0)
	v_cvt_pk_bf16_f32 v4, v4, v5
	ds_read2_b32 v[6:7], v48 offset0:222 offset1:255
	v_lshlrev_b64 v[10:11], 13, v[10:11]
	s_waitcnt lgkmcnt(0)
	v_cvt_pk_bf16_f32 v5, v6, v7
	v_lshl_add_u64 v[6:7], v[8:9], 0, v[10:11]
	global_store_dwordx4 v[6:7], v[2:5], off
	s_waitcnt lgkmcnt(0)
	s_branch .LBB0_10
.LBB0_45:
	s_cmpk_gt_i32 s8, 0x47ff
	v_mov_b32_e32 v67, 0
	s_cbranch_scc1 .LBB0_50
	v_mbcnt_lo_u32_b32 v1, -1, 0
	v_mbcnt_hi_u32_b32 v2, -1, v1
	v_and_b32_e32 v1, 64, v2
	v_add_u32_e32 v3, 64, v1
	v_xor_b32_e32 v1, 1, v2
	v_cmp_lt_i32_e32 vcc, v1, v3
	v_xor_b32_e32 v4, 2, v2
	v_lshlrev_b32_e32 v66, 3, v196
	v_cndmask_b32_e32 v1, v2, v1, vcc
	v_cmp_lt_i32_e32 vcc, v4, v3
	v_lshl_add_u64 v[68:69], s[86:87], 0, v[66:67]
	v_lshlrev_b32_e32 v66, 4, v196
	v_cndmask_b32_e32 v4, v2, v4, vcc
	v_lshlrev_b32_e32 v96, 2, v4
	v_xor_b32_e32 v4, 4, v2
	v_cmp_lt_i32_e32 vcc, v4, v3
	v_lshl_add_u64 v[70:71], s[64:65], 0, v[66:67]
	s_mov_b64 s[0:1], 0x1000
	v_cndmask_b32_e32 v4, v2, v4, vcc
	v_lshl_add_u64 v[72:73], v[70:71], 0, s[0:1]
	s_mov_b64 s[0:1], 0x1400
	v_lshlrev_b32_e32 v97, 2, v4
	v_xor_b32_e32 v4, 8, v2
	v_lshl_add_u64 v[74:75], v[70:71], 0, s[0:1]
	s_mov_b64 s[0:1], 0x1800
	v_cmp_lt_i32_e32 vcc, v4, v3
	v_lshl_add_u64 v[76:77], v[70:71], 0, s[0:1]
	s_mov_b64 s[0:1], 0x1c00
	v_cndmask_b32_e32 v4, v2, v4, vcc
	v_lshl_add_u64 v[78:79], v[70:71], 0, s[0:1]
	s_mov_b64 s[0:1], 0x2000
	v_lshlrev_b32_e32 v98, 2, v4
	v_xor_b32_e32 v4, 16, v2
	v_lshl_add_u64 v[80:81], v[70:71], 0, s[0:1]
	s_mov_b64 s[0:1], 0x2400
	v_cmp_lt_i32_e32 vcc, v4, v3
	v_lshl_add_u64 v[82:83], v[70:71], 0, s[0:1]
	s_mov_b64 s[0:1], 0x2800
	v_cndmask_b32_e32 v4, v2, v4, vcc
	v_lshl_add_u64 v[84:85], v[70:71], 0, s[0:1]
	s_mov_b64 s[0:1], 0x2c00
	v_lshlrev_b32_e32 v99, 2, v4
	v_xor_b32_e32 v4, 32, v2
	v_lshl_add_u64 v[86:87], v[70:71], 0, s[0:1]
	s_mov_b64 s[0:1], 0x3000
	v_cmp_lt_i32_e32 vcc, v4, v3
	v_lshl_add_u64 v[88:89], v[70:71], 0, s[0:1]
	s_mov_b64 s[0:1], 0x3400
	v_cndmask_b32_e32 v2, v2, v4, vcc
	v_lshl_add_u64 v[90:91], v[70:71], 0, s[0:1]
	s_mov_b64 s[0:1], 0x3800
	s_ashr_i32 s9, s8, 31
	v_lshlrev_b32_e32 v100, 2, v2
	v_lshl_add_u64 v[92:93], v[70:71], 0, s[0:1]
	v_mov_b32_e32 v2, 0x3c00
	s_ashr_i32 s11, s10, 31
	s_lshl_b64 s[0:1], s[8:9], 14
	v_lshl_or_b32 v2, v0, 4, v2
	v_mov_b32_e32 v3, v67
	s_add_u32 s12, s52, s0
	s_mov_b32 s5, 0
	v_lshlrev_b32_e32 v1, 2, v1
	v_lshl_add_u64 v[94:95], s[64:65], 0, v[2:3]
	s_addc_u32 s13, s53, s1
	s_lshl_b64 s[14:15], s[10:11], 14
	s_movk_i32 s20, 0x1000
	s_movk_i32 s21, 0x2000
	s_movk_i32 s28, 0x3000
	v_mov_b32_e32 v101, 0x358637bd
	s_mov_b32 s29, 0xf800000
	v_mov_b32_e32 v102, 0x260
	s_mov_b64 s[16:17], s[8:9]
	s_branch .LBB0_48
